# attention A NA+MEM loops: waves 4-7 take the per-tile barrier mid-step (after QK^T and LDS reads) so SIMD partners overlap matrix and vector work
# speedup vs baseline: 1.0036x; 1.0036x over previous
.LBB0_475:
	s_lshl_b32 s0, s59, 14
	s_xor_b64 s[10:11], s[10:11], -1
	v_add_u32_e32 v201, s0, v204
	v_add_u32_e32 v202, s0, v215
	v_xor_b32_e32 v0, 32, v201
	v_xor_b32_e32 v95, 64, v201
	ds_read_b128 v[66:69], v201
	ds_read_b128 v[216:219], v0
	v_xor_b32_e32 v0, 0x60, v201
	ds_read_b128 v[220:223], v95
	v_xor_b32_e32 v95, 0x80, v201
	ds_read_b128 v[224:227], v0
	v_xor_b32_e32 v0, 0xa0, v201
	ds_read_b128 v[228:231], v95
	v_xor_b32_e32 v95, 0xc0, v201
	ds_read_b128 v[232:235], v0
	v_xor_b32_e32 v0, 0xe0, v201
	ds_read_b128 v[236:239], v95
	ds_read_b128 v[240:243], v0
	s_waitcnt lgkmcnt(7)
	v_mfma_f32_32x32x16_bf16 v[66:81], v[66:69], v[82:85], 0
	v_and_b32_e32 v251, 64, v207
	v_xor_b32_e32 v250, 32, v207
	v_add_u32_e32 v251, 64, v251
	v_cmp_lt_i32_e32 vcc, v250, v251
	s_nop 1
	v_cndmask_b32_e32 v250, v207, v250, vcc
	v_lshlrev_b32_e32 v200, 2, v250
	s_waitcnt lgkmcnt(6)
	v_mfma_f32_32x32x16_bf16 v[66:81], v[216:219], v[86:89], v[66:81]
	s_waitcnt lgkmcnt(5)
	v_mfma_f32_32x32x16_bf16 v[66:81], v[220:223], v[90:93], v[66:81]
	s_waitcnt lgkmcnt(4)
	v_mfma_f32_32x32x16_bf16 v[66:81], v[224:227], v[128:131], v[66:81]
	s_waitcnt lgkmcnt(3)
	v_mfma_f32_32x32x16_bf16 v[66:81], v[228:231], v[132:135], v[66:81]
	s_waitcnt lgkmcnt(2)
	v_mfma_f32_32x32x16_bf16 v[66:81], v[232:235], v[136:139], v[66:81]
	s_waitcnt lgkmcnt(1)
	v_mfma_f32_32x32x16_bf16 v[66:81], v[236:239], v[140:143], v[66:81]
	s_waitcnt lgkmcnt(0)
	v_mfma_f32_32x32x16_bf16 v[66:81], v[240:243], v[144:147], v[66:81]
	v_xor_b32_e32 v0, 0x820, v202
	v_xor_b32_e32 v95, 64, v202
	v_xor_b32_e32 v203, 0x860, v202
	v_xor_b32_e32 v244, 0x80, v202
	v_xor_b32_e32 v245, 0x8a0, v202
	v_xor_b32_e32 v246, 0xc0, v202
	v_xor_b32_e32 v247, 0x8e0, v202
	ds_read_b64_tr_b16 v[216:217], v202
	ds_read_b64_tr_b16 v[218:219], v0
	ds_read_b64_tr_b16 v[220:221], v95
	ds_read_b64_tr_b16 v[222:223], v203
	ds_read_b64_tr_b16 v[224:225], v244
	ds_read_b64_tr_b16 v[226:227], v245
	ds_read_b64_tr_b16 v[248:249], v246
	ds_read_b64_tr_b16 v[250:251], v247
	ds_read_b64_tr_b16 v[228:229], v202 offset:4096
	ds_read_b64_tr_b16 v[230:231], v0 offset:4096
	ds_read_b64_tr_b16 v[232:233], v95 offset:4096
	ds_read_b64_tr_b16 v[234:235], v203 offset:4096
	ds_read_b64_tr_b16 v[236:237], v244 offset:4096
	ds_read_b64_tr_b16 v[238:239], v245 offset:4096
	ds_read_b64_tr_b16 v[240:241], v246 offset:4096
	ds_read_b64_tr_b16 v[242:243], v247 offset:4096
	s_cmp_lt_u32 s95, 4
	s_cbranch_scc1 .Lmem_mid_skip
	s_cmp_eq_u64 s[10:11], 0
	s_cbranch_scc1 .Lmem_mid_w0
	s_waitcnt vmcnt(4)
	s_branch .Lmem_mid_bar

.Lmem_mid_bar:
	s_waitcnt lgkmcnt(0)
	s_barrier
.Lmem_mid_skip:
	v_max3_f32 v0, v66, v67, v68
	v_max3_f32 v95, v69, v70, v71
	v_max3_f32 v201, v72, v73, v74
	v_max3_f32 v0, v0, v75, v76
	v_max3_f32 v95, v95, v77, v78
	v_max3_f32 v201, v201, v79, v80
	v_max3_f32 v0, v0, v95, v201
	v_max_f32_e32 v0, v0, v81
	v_mov_b32_e32 v95, v0
	s_nop 1
	v_permlane32_swap_b32_e32 v95, v0
	s_nop 0
	v_max3_f32 v95, v199, v0, v95
	v_sub_f32_e32 v0, v199, v95
	v_exp_f32_e32 v0, v0
	v_sub_f32_e32 v66, v66, v95
	v_sub_f32_e32 v67, v67, v95
	v_exp_f32_e32 v66, v66
	v_sub_f32_e32 v68, v68, v95
	v_exp_f32_e32 v67, v67
	v_sub_f32_e32 v69, v69, v95
	v_exp_f32_e32 v68, v68
	v_sub_f32_e32 v70, v70, v95
	v_add_f32_e32 v201, v67, v66
	v_exp_f32_e32 v69, v69
	v_sub_f32_e32 v71, v71, v95
	v_add_f32_e32 v201, v68, v201
	v_exp_f32_e32 v70, v70
	v_sub_f32_e32 v72, v72, v95
	v_add_f32_e32 v201, v69, v201
	v_exp_f32_e32 v71, v71
	v_sub_f32_e32 v73, v73, v95
	v_add_f32_e32 v201, v70, v201
	v_exp_f32_e32 v72, v72
	v_sub_f32_e32 v74, v74, v95
	v_add_f32_e32 v201, v71, v201
	v_exp_f32_e32 v73, v73
	v_sub_f32_e32 v75, v75, v95
	v_add_f32_e32 v201, v72, v201
	v_exp_f32_e32 v74, v74
	v_sub_f32_e32 v76, v76, v95
	v_add_f32_e32 v201, v73, v201
	v_exp_f32_e32 v75, v75
	v_sub_f32_e32 v77, v77, v95
	v_add_f32_e32 v201, v74, v201
	v_exp_f32_e32 v76, v76
	v_sub_f32_e32 v78, v78, v95
	v_add_f32_e32 v201, v75, v201
	v_exp_f32_e32 v77, v77
	v_sub_f32_e32 v79, v79, v95
	v_add_f32_e32 v201, v76, v201
	v_exp_f32_e32 v78, v78
	v_sub_f32_e32 v80, v80, v95
	v_add_f32_e32 v201, v77, v201
	v_exp_f32_e32 v79, v79
	v_sub_f32_e32 v81, v81, v95
	v_add_f32_e32 v201, v78, v201
	v_exp_f32_e32 v80, v80
	v_add_f32_e32 v201, v79, v201
	v_exp_f32_e32 v81, v81
	v_add_f32_e32 v201, v80, v201
	v_add_f32_e32 v201, v81, v201
	v_fmac_f32_e32 v201, v198, v0
	v_cvt_pk_bf16_f32 v244, v66, v67
	v_cvt_pk_bf16_f32 v245, v68, v69
	v_cvt_pk_bf16_f32 v246, v70, v71
	v_cvt_pk_bf16_f32 v247, v72, v73
	v_cvt_pk_bf16_f32 v66, v74, v75
	v_cvt_pk_bf16_f32 v67, v76, v77
	v_cvt_pk_bf16_f32 v68, v78, v79
	v_cvt_pk_bf16_f32 v69, v80, v81
	s_waitcnt lgkmcnt(8)
	v_pk_mul_f32 v[50:51], v[50:51], v[0:1] op_sel_hi:[1,0]
	v_pk_mul_f32 v[52:53], v[52:53], v[0:1] op_sel_hi:[1,0]
	v_pk_mul_f32 v[54:55], v[54:55], v[0:1] op_sel_hi:[1,0]
	v_pk_mul_f32 v[56:57], v[56:57], v[0:1] op_sel_hi:[1,0]
	v_pk_mul_f32 v[58:59], v[58:59], v[0:1] op_sel_hi:[1,0]
	v_pk_mul_f32 v[60:61], v[60:61], v[0:1] op_sel_hi:[1,0]
	v_pk_mul_f32 v[62:63], v[62:63], v[0:1] op_sel_hi:[1,0]
	v_pk_mul_f32 v[64:65], v[64:65], v[0:1] op_sel_hi:[1,0]
	v_pk_mul_f32 v[34:35], v[34:35], v[0:1] op_sel_hi:[1,0]
	v_pk_mul_f32 v[36:37], v[36:37], v[0:1] op_sel_hi:[1,0]
	v_mfma_f32_32x32x16_bf16 v[50:65], v[216:219], v[244:247], v[50:65]
	v_pk_mul_f32 v[38:39], v[38:39], v[0:1] op_sel_hi:[1,0]
	v_pk_mul_f32 v[40:41], v[40:41], v[0:1] op_sel_hi:[1,0]
	v_pk_mul_f32 v[42:43], v[42:43], v[0:1] op_sel_hi:[1,0]
	v_pk_mul_f32 v[44:45], v[44:45], v[0:1] op_sel_hi:[1,0]
	v_pk_mul_f32 v[46:47], v[46:47], v[0:1] op_sel_hi:[1,0]
	v_pk_mul_f32 v[48:49], v[48:49], v[0:1] op_sel_hi:[1,0]
	v_pk_mul_f32 v[18:19], v[18:19], v[0:1] op_sel_hi:[1,0]
	v_pk_mul_f32 v[20:21], v[20:21], v[0:1] op_sel_hi:[1,0]
	v_mfma_f32_32x32x16_bf16 v[34:49], v[220:223], v[244:247], v[34:49]
	v_pk_mul_f32 v[22:23], v[22:23], v[0:1] op_sel_hi:[1,0]
	v_pk_mul_f32 v[24:25], v[24:25], v[0:1] op_sel_hi:[1,0]
	v_pk_mul_f32 v[26:27], v[26:27], v[0:1] op_sel_hi:[1,0]
	v_pk_mul_f32 v[28:29], v[28:29], v[0:1] op_sel_hi:[1,0]
	v_pk_mul_f32 v[30:31], v[30:31], v[0:1] op_sel_hi:[1,0]
	v_pk_mul_f32 v[32:33], v[32:33], v[0:1] op_sel_hi:[1,0]
	v_pk_mul_f32 v[2:3], v[2:3], v[0:1] op_sel_hi:[1,0]
	v_pk_mul_f32 v[4:5], v[4:5], v[0:1] op_sel_hi:[1,0]
	v_mfma_f32_32x32x16_bf16 v[18:33], v[224:227], v[244:247], v[18:33]
	v_pk_mul_f32 v[6:7], v[6:7], v[0:1] op_sel_hi:[1,0]
	v_pk_mul_f32 v[8:9], v[8:9], v[0:1] op_sel_hi:[1,0]
	v_pk_mul_f32 v[10:11], v[10:11], v[0:1] op_sel_hi:[1,0]
	v_pk_mul_f32 v[12:13], v[12:13], v[0:1] op_sel_hi:[1,0]
	v_pk_mul_f32 v[14:15], v[14:15], v[0:1] op_sel_hi:[1,0]
	v_pk_mul_f32 v[16:17], v[16:17], v[0:1] op_sel_hi:[1,0]
	v_mov_b32_e32 v198, v201
	v_mov_b32_e32 v199, v95
	v_mfma_f32_32x32x16_bf16 v[2:17], v[248:251], v[244:247], v[2:17]
	s_waitcnt lgkmcnt(0)
	v_mfma_f32_32x32x16_bf16 v[50:65], v[228:231], v[66:69], v[50:65]
	v_mfma_f32_32x32x16_bf16 v[34:49], v[232:235], v[66:69], v[34:49]
	v_mfma_f32_32x32x16_bf16 v[18:33], v[236:239], v[66:69], v[18:33]
	v_mfma_f32_32x32x16_bf16 v[2:17], v[240:243], v[66:69], v[2:17]
	v_mov_b32_e32 v68, v201
	s_mov_b64 s[0:1], -1
	s_andn2_b64 vcc, exec, s[10:11]
	s_cbranch_vccnz .LBB0_479
	s_waitcnt vmcnt(4)
	s_mov_b64 s[0:1], 0

.LBB0_481:
	s_cmp_gt_u32 s95, 3
	s_cbranch_scc1 .Lmem_late_bot
	s_add_i32 s0, s59, 1
	s_cmp_lg_u32 s0, 6
	s_cselect_b32 s59, s0, 0
	s_bitcmp1_b32 s21, 0
	s_waitcnt lgkmcnt(0)
	s_barrier
.Lmem_bot_join:
	s_cselect_b64 s[10:11], -1, 0
	s_add_i32 s24, s24, -1
	s_cmp_eq_u32 s24, 0
	s_cbranch_scc0 .LBB0_442
	ds_bpermute_b32 v69, v200, v68

.LBB0_497:
	s_mov_b32 s101, 0
	s_mul_hi_i32 s0, s58, 0x2aaaaaab
	s_lshr_b32 s1, s0, 31
	s_ashr_i32 s0, s0, 3
	s_add_i32 s20, s0, s1
	s_mul_i32 s0, s20, 48
	s_sub_i32 s10, s58, s0
	s_lshl_b32 s1, s10, 2
	s_and_b32 s0, s1, 28
	v_sub_u32_e64 v0, s0, 1 clamp
	s_max_u32 s19, s0, 4
	v_readfirstlane_b32 s11, v0
	s_min_u32 s21, s11, 24
	v_readlane_b32 s11, v254, 28
	s_or_b32 s16, s0, s11
	s_ashr_i32 s17, s10, 3
	s_sub_i32 s10, s21, s19
	s_cmp_lt_i32 s10, -11
	s_waitcnt vmcnt(8) lgkmcnt(0)
	s_cbranch_scc1 .LBB0_607
	v_sub_u32_e64 v0, s16, 4 clamp
	v_min_u32_e32 v130, 24, v0
	v_add_u32_e32 v0, s0, v196
	v_sub_u32_e64 v2, s16, 3 clamp
	s_mul_i32 s10, s17, 0x744
	s_mul_i32 s11, s19, 0x7c
	s_bfe_u32 s1, s1, 0x30002
	v_sub_u32_e64 v0, v0, 4 clamp
	v_min_u32_e32 v2, 24, v2
	s_add_i32 s10, s10, s11
	s_mulk_i32 s1, 0x1f0
	v_min_u32_e32 v0, 24, v0
	v_mov_b32_e32 v14, v1
	v_mov_b32_e32 v15, v1
	v_add_u32_e32 v129, 8, v2
	s_sub_i32 s1, s10, s1
	v_sub_u32_e32 v132, -4, v0
	v_mov_b32_e32 v0, v1
	v_mov_b32_e32 v2, v1
	v_mov_b32_e32 v3, v1
	v_mov_b32_e32 v4, v1
	v_mov_b32_e32 v5, v1
	v_mov_b32_e32 v6, v1
	v_mov_b32_e32 v7, v1
	v_mov_b32_e32 v8, v1
	v_mov_b32_e32 v9, v1
	v_mov_b32_e32 v10, v1
	v_mov_b32_e32 v11, v1
	v_mov_b32_e32 v12, v1
	v_mov_b32_e32 v13, v1
	v_mov_b64_e32 v[78:79], v[14:15]
	v_mov_b64_e32 v[62:63], v[14:15]
	v_mov_b64_e32 v[46:47], v[14:15]
	v_mov_b64_e32 v[30:31], v[14:15]
	s_add_i32 s21, s21, 12
	v_add_u32_e32 v131, s1, v195
	v_mov_b32_e32 v133, 0xc61c4000
	v_mov_b32_e32 v128, 0
	s_mov_b32 s98, s61
	v_mov_b64_e32 v[76:77], v[12:13]
	v_mov_b64_e32 v[74:75], v[10:11]
	v_mov_b64_e32 v[72:73], v[8:9]
	v_mov_b64_e32 v[70:71], v[6:7]
	v_mov_b64_e32 v[68:69], v[4:5]
	v_mov_b64_e32 v[66:67], v[2:3]
	v_mov_b64_e32 v[64:65], v[0:1]
	v_mov_b64_e32 v[60:61], v[12:13]
	v_mov_b64_e32 v[58:59], v[10:11]
	v_mov_b64_e32 v[56:57], v[8:9]
	v_mov_b64_e32 v[54:55], v[6:7]
	v_mov_b64_e32 v[52:53], v[4:5]
	v_mov_b64_e32 v[50:51], v[2:3]
	v_mov_b64_e32 v[48:49], v[0:1]
	v_mov_b64_e32 v[44:45], v[12:13]
	v_mov_b64_e32 v[42:43], v[10:11]
	v_mov_b64_e32 v[40:41], v[8:9]
	v_mov_b64_e32 v[38:39], v[6:7]
	v_mov_b64_e32 v[36:37], v[4:5]
	v_mov_b64_e32 v[34:35], v[2:3]
	v_mov_b64_e32 v[32:33], v[0:1]
	v_mov_b64_e32 v[28:29], v[12:13]
	v_mov_b64_e32 v[26:27], v[10:11]
	v_mov_b64_e32 v[24:25], v[8:9]
	v_mov_b64_e32 v[22:23], v[6:7]
	v_mov_b64_e32 v[20:21], v[4:5]
	v_mov_b64_e32 v[18:19], v[2:3]
	v_mov_b64_e32 v[16:17], v[0:1]
	v_and_b32_e32 v232, 31, v169
	v_add_u32_e32 v232, s18, v232
	v_lshrrev_b32_e32 v233, 5, v169
	v_lshlrev_b32_e32 v234, 2, v232
	v_and_b32_e32 v234, 12, v234
	v_bfe_u32 v235, v232, 2, 2
	v_or_b32_e32 v234, v234, v235
	v_xor_b32_e32 v234, v233, v234
	v_lshlrev_b32_e32 v234, 4, v234
	v_lshl_add_u32 v248, v232, 8, v234
	v_lshl_add_u32 v232, v233, 2, s18
	v_lshrrev_b32_e32 v234, 2, v169
	v_and_or_b32 v232, v234, 3, v232
	v_bfe_u32 v234, v169, 1, 1
	v_lshrrev_b32_e32 v235, 3, v169
	v_and_or_b32 v234, v235, 2, v234
	v_lshlrev_b32_e32 v235, 3, v169
	v_and_b32_e32 v235, 8, v235
	v_lshlrev_b32_e32 v236, 2, v232
	v_and_b32_e32 v236, 12, v236
	v_bfe_u32 v251, v232, 2, 2
	v_or_b32_e32 v236, v236, v251
	v_xor_b32_e32 v236, v234, v236
	v_lshlrev_b32_e32 v236, 4, v236
	v_lshl_add_u32 v236, v232, 8, v236
	v_add_u32_e32 v249, v236, v235
	v_add_u32_e32 v232, 8, v232
	v_lshlrev_b32_e32 v236, 2, v232
	v_and_b32_e32 v236, 12, v236
	v_bfe_u32 v251, v232, 2, 2
	v_or_b32_e32 v236, v236, v251
	v_xor_b32_e32 v236, v234, v236
	v_lshlrev_b32_e32 v236, 4, v236
	v_lshl_add_u32 v236, v232, 8, v236
	v_add_u32_e32 v250, v236, v235

.LBB0_565:
	s_add_i32 s0, s19, -4
	v_cmp_ge_u32_e32 vcc, s0, v130
	v_cmp_lt_u32_e64 s[12:13], s0, v129
	s_and_b64 s[0:1], vcc, s[12:13]
	s_andn2_b64 vcc, exec, s[0:1]
	s_cbranch_vccnz .LBB0_602
	s_lshl_b32 s0, s64, 14
	s_add_i32 s1, s64, 1
	s_cmp_lg_u32 s1, 6
	s_cselect_b32 s1, s1, 0
	s_lshl_b32 s1, s1, 14
	v_add_u32_e32 v251, s0, v248
	v_xor_b32_e32 v0, 32, v251
	v_xor_b32_e32 v2, 64, v251
	ds_read_b128 v[4:7], v251
	ds_read_b128 v[8:11], v0
	v_xor_b32_e32 v0, 0x60, v251
	ds_read_b128 v[12:15], v2
	v_xor_b32_e32 v2, 0x80, v251
	ds_read_b128 v[134:137], v0
	v_xor_b32_e32 v0, 0xa0, v251
	ds_read_b128 v[138:141], v2
	v_xor_b32_e32 v2, 0xc0, v251
	ds_read_b128 v[142:145], v0
	v_xor_b32_e32 v0, 0xe0, v251
	ds_read_b128 v[198:201], v2
	ds_read_b128 v[216:219], v0
	ds_read2_b32 v[232:233], v131 offset1:1
	ds_read2_b32 v[234:235], v131 offset0:2 offset1:3
	ds_read2_b32 v[236:237], v131 offset0:8 offset1:9
	ds_read2_b32 v[238:239], v131 offset0:10 offset1:11
	ds_read2_b32 v[240:241], v131 offset0:16 offset1:17
	ds_read2_b32 v[242:243], v131 offset0:18 offset1:19
	ds_read2_b32 v[244:245], v131 offset0:24 offset1:25
	s_waitcnt lgkmcnt(14)
	v_mfma_f32_32x32x16_bf16 v[80:95], v[4:7], v[124:127], 0
	ds_read2_b32 v[246:247], v131 offset0:26 offset1:27
	v_add_u32_e32 v0, s19, v132
	v_cmp_gt_u32_e32 vcc, 8, v0
	v_add_u32_e32 v2, s1, v249
	v_add_u32_e32 v3, s1, v250
	v_cndmask_b32_e32 v0, v212, v187, vcc
	s_waitcnt lgkmcnt(14)
	v_mfma_f32_32x32x16_bf16 v[80:95], v[8:11], v[120:123], v[80:95]
	s_waitcnt lgkmcnt(13)
	v_mfma_f32_32x32x16_bf16 v[80:95], v[12:15], v[116:119], v[80:95]
	s_waitcnt lgkmcnt(12)
	v_mfma_f32_32x32x16_bf16 v[80:95], v[134:137], v[112:115], v[80:95]
	s_waitcnt lgkmcnt(11)
	v_mfma_f32_32x32x16_bf16 v[80:95], v[138:141], v[108:111], v[80:95]
	s_waitcnt lgkmcnt(10)
	v_mfma_f32_32x32x16_bf16 v[80:95], v[142:145], v[104:107], v[80:95]
	s_waitcnt lgkmcnt(9)
	v_mfma_f32_32x32x16_bf16 v[80:95], v[198:201], v[100:103], v[80:95]
	s_waitcnt lgkmcnt(8)
	v_mfma_f32_32x32x16_bf16 v[80:95], v[216:219], v[96:99], v[80:95]
	v_xor_b32_e32 v4, 64, v2
	v_xor_b32_e32 v5, 64, v3
	v_xor_b32_e32 v6, 0x80, v2
	v_xor_b32_e32 v7, 0x80, v3
	v_xor_b32_e32 v8, 0xc0, v2
	v_xor_b32_e32 v9, 0xc0, v3
	ds_read_b64_tr_b16 v[220:221], v2
	ds_read_b64_tr_b16 v[222:223], v3
	ds_read_b64_tr_b16 v[224:225], v4
	ds_read_b64_tr_b16 v[226:227], v5
	ds_read_b64_tr_b16 v[228:229], v6
	ds_read_b64_tr_b16 v[230:231], v7
	ds_read_b64_tr_b16 v[198:199], v8
	ds_read_b64_tr_b16 v[200:201], v9
	s_waitcnt lgkmcnt(8)
	v_cmp_gt_u32_e32 vcc, 16, v0
	v_add_f32_e32 v232, v80, v232
	v_add_u32_e32 v251, 1, v0
	v_cmp_gt_u32_e64 s[0:1], 16, v251
	v_add_f32_e32 v233, v81, v233
	v_cndmask_b32_e32 v80, v210, v232, vcc
	v_add_u32_e32 v251, 2, v0
	v_cmp_gt_u32_e32 vcc, 16, v251
	v_add_f32_e32 v234, v82, v234
	v_cndmask_b32_e64 v81, v210, v233, s[0:1]
	v_add_u32_e32 v251, 3, v0
	v_cmp_gt_u32_e64 s[0:1], 16, v251
	v_add_f32_e32 v235, v83, v235
	v_cndmask_b32_e32 v82, v210, v234, vcc
	v_add_u32_e32 v251, 8, v0
	v_cmp_gt_u32_e32 vcc, 16, v251
	v_add_f32_e32 v236, v84, v236
	v_cndmask_b32_e64 v83, v210, v235, s[0:1]
	v_add_u32_e32 v251, 9, v0
	v_cmp_gt_u32_e64 s[0:1], 16, v251
	v_add_f32_e32 v237, v85, v237
	v_cndmask_b32_e32 v84, v210, v236, vcc
	v_add_u32_e32 v251, 10, v0
	v_cmp_gt_u32_e32 vcc, 16, v251
	v_add_f32_e32 v238, v86, v238
	v_cndmask_b32_e64 v85, v210, v237, s[0:1]
	v_add_u32_e32 v251, 11, v0
	v_cmp_gt_u32_e64 s[0:1], 16, v251
	v_add_f32_e32 v239, v87, v239
	v_cndmask_b32_e32 v86, v210, v238, vcc
	v_add_u32_e32 v251, 16, v0
	v_cmp_gt_u32_e32 vcc, 16, v251
	v_add_f32_e32 v240, v88, v240
	v_cndmask_b32_e64 v87, v210, v239, s[0:1]
	v_add_u32_e32 v251, 17, v0
	v_cmp_gt_u32_e64 s[0:1], 16, v251
	v_add_f32_e32 v241, v89, v241
	v_cndmask_b32_e32 v88, v210, v240, vcc
	v_add_u32_e32 v251, 18, v0
	v_cmp_gt_u32_e32 vcc, 16, v251
	v_add_f32_e32 v242, v90, v242
	v_cndmask_b32_e64 v89, v210, v241, s[0:1]
	v_add_u32_e32 v251, 19, v0
	v_cmp_gt_u32_e64 s[0:1], 16, v251
	v_add_f32_e32 v243, v91, v243
	v_cndmask_b32_e32 v90, v210, v242, vcc
	v_add_u32_e32 v251, 24, v0
	v_cmp_gt_u32_e32 vcc, 16, v251
	v_add_f32_e32 v244, v92, v244
	v_cndmask_b32_e64 v91, v210, v243, s[0:1]
	v_add_u32_e32 v251, 25, v0
	v_cmp_gt_u32_e64 s[0:1], 16, v251
	v_add_f32_e32 v245, v93, v245
	v_cndmask_b32_e32 v92, v210, v244, vcc
	v_add_u32_e32 v251, 26, v0
	v_cmp_gt_u32_e32 vcc, 16, v251
	v_add_f32_e32 v246, v94, v246
	v_cndmask_b32_e64 v93, v210, v245, s[0:1]
	v_add_u32_e32 v251, 27, v0
	v_cmp_gt_u32_e64 s[0:1], 16, v251
	v_add_f32_e32 v247, v95, v247
	v_cndmask_b32_e32 v94, v210, v246, vcc
	s_nop 1
	v_cndmask_b32_e64 v95, v210, v247, s[0:1]
	ds_read_b64_tr_b16 v[232:233], v2 offset:4096
	ds_read_b64_tr_b16 v[234:235], v3 offset:4096
	ds_read_b64_tr_b16 v[236:237], v4 offset:4096
	ds_read_b64_tr_b16 v[238:239], v5 offset:4096
	ds_read_b64_tr_b16 v[240:241], v6 offset:4096
	ds_read_b64_tr_b16 v[242:243], v7 offset:4096
	ds_read_b64_tr_b16 v[244:245], v8 offset:4096
	ds_read_b64_tr_b16 v[246:247], v9 offset:4096
	s_cmp_lt_u32 s95, 4
	s_cbranch_scc1 .Lna_mid_skip
	s_or_b32 s100, s24, s56
	s_and_b32 s100, s100, 0xff
	s_cmp_lg_u32 s100, 0
	s_cbranch_scc1 .Lna_mid_w0
	s_waitcnt vmcnt(4)
	s_branch .Lna_mid_bar

.Lna_mid_bar:
	s_waitcnt lgkmcnt(0)
	s_barrier
	s_mov_b32 s101, 1
.Lna_mid_skip:
	v_max3_f32 v0, v80, v81, v82
	v_max3_f32 v4, v83, v84, v85
	v_max3_f32 v215, v86, v87, v88
	v_max3_f32 v0, v0, v89, v90
	v_max3_f32 v4, v4, v91, v92
	v_max3_f32 v215, v215, v93, v94
	v_max3_f32 v0, v0, v4, v215
	v_max_f32_e32 v0, v0, v95
	v_mov_b32_e32 v4, v0
	s_nop 1
	v_permlane32_swap_b32_e32 v4, v0
	s_nop 0
	v_max3_f32 v4, v133, v0, v4
	v_sub_f32_e32 v0, v133, v4
	v_exp_f32_e32 v0, v0
	v_sub_f32_e32 v80, v80, v4
	v_sub_f32_e32 v81, v81, v4
	v_exp_f32_e32 v80, v80
	v_sub_f32_e32 v82, v82, v4
	v_exp_f32_e32 v81, v81
	v_sub_f32_e32 v83, v83, v4
	v_exp_f32_e32 v82, v82
	v_sub_f32_e32 v84, v84, v4
	v_add_f32_e32 v215, v81, v80
	v_exp_f32_e32 v83, v83
	v_sub_f32_e32 v85, v85, v4
	v_add_f32_e32 v215, v82, v215
	v_exp_f32_e32 v84, v84
	v_sub_f32_e32 v86, v86, v4
	v_add_f32_e32 v215, v83, v215
	v_exp_f32_e32 v85, v85
	v_sub_f32_e32 v87, v87, v4
	v_add_f32_e32 v215, v84, v215
	v_exp_f32_e32 v86, v86
	v_sub_f32_e32 v88, v88, v4
	v_add_f32_e32 v215, v85, v215
	v_exp_f32_e32 v87, v87
	v_sub_f32_e32 v89, v89, v4
	v_add_f32_e32 v215, v86, v215
	v_exp_f32_e32 v88, v88
	v_sub_f32_e32 v90, v90, v4
	v_add_f32_e32 v215, v87, v215
	v_exp_f32_e32 v89, v89
	v_sub_f32_e32 v91, v91, v4
	v_add_f32_e32 v215, v88, v215
	v_exp_f32_e32 v90, v90
	v_sub_f32_e32 v92, v92, v4
	v_add_f32_e32 v215, v89, v215
	v_exp_f32_e32 v91, v91
	v_sub_f32_e32 v93, v93, v4
	v_add_f32_e32 v215, v90, v215
	v_exp_f32_e32 v92, v92
	v_sub_f32_e32 v94, v94, v4
	v_add_f32_e32 v215, v91, v215
	v_exp_f32_e32 v93, v93
	v_sub_f32_e32 v95, v95, v4
	v_add_f32_e32 v215, v92, v215
	v_exp_f32_e32 v94, v94
	v_add_f32_e32 v215, v93, v215
	v_exp_f32_e32 v95, v95
	v_add_f32_e32 v215, v94, v215
	v_add_f32_e32 v215, v95, v215
	v_fmac_f32_e32 v215, v128, v0
	v_cvt_pk_bf16_f32 v8, v80, v81
	v_cvt_pk_bf16_f32 v9, v82, v83
	v_cvt_pk_bf16_f32 v10, v84, v85
	v_cvt_pk_bf16_f32 v11, v86, v87
	v_cvt_pk_bf16_f32 v12, v88, v89
	v_cvt_pk_bf16_f32 v13, v90, v91
	v_cvt_pk_bf16_f32 v14, v92, v93
	v_cvt_pk_bf16_f32 v15, v94, v95
	s_waitcnt lgkmcnt(8)
	v_pk_mul_f32 v[64:65], v[64:65], v[0:1] op_sel_hi:[1,0]
	v_pk_mul_f32 v[66:67], v[66:67], v[0:1] op_sel_hi:[1,0]
	v_pk_mul_f32 v[68:69], v[68:69], v[0:1] op_sel_hi:[1,0]
	v_pk_mul_f32 v[70:71], v[70:71], v[0:1] op_sel_hi:[1,0]
	v_pk_mul_f32 v[72:73], v[72:73], v[0:1] op_sel_hi:[1,0]
	v_pk_mul_f32 v[74:75], v[74:75], v[0:1] op_sel_hi:[1,0]
	v_pk_mul_f32 v[76:77], v[76:77], v[0:1] op_sel_hi:[1,0]
	v_pk_mul_f32 v[78:79], v[78:79], v[0:1] op_sel_hi:[1,0]
	v_pk_mul_f32 v[48:49], v[48:49], v[0:1] op_sel_hi:[1,0]
	v_pk_mul_f32 v[50:51], v[50:51], v[0:1] op_sel_hi:[1,0]
	v_mfma_f32_32x32x16_bf16 v[64:79], v[220:223], v[8:11], v[64:79]
	v_pk_mul_f32 v[52:53], v[52:53], v[0:1] op_sel_hi:[1,0]
	v_pk_mul_f32 v[54:55], v[54:55], v[0:1] op_sel_hi:[1,0]
	v_pk_mul_f32 v[56:57], v[56:57], v[0:1] op_sel_hi:[1,0]
	v_pk_mul_f32 v[58:59], v[58:59], v[0:1] op_sel_hi:[1,0]
	v_pk_mul_f32 v[60:61], v[60:61], v[0:1] op_sel_hi:[1,0]
	v_pk_mul_f32 v[62:63], v[62:63], v[0:1] op_sel_hi:[1,0]
	v_pk_mul_f32 v[32:33], v[32:33], v[0:1] op_sel_hi:[1,0]
	v_pk_mul_f32 v[34:35], v[34:35], v[0:1] op_sel_hi:[1,0]
	v_mfma_f32_32x32x16_bf16 v[48:63], v[224:227], v[8:11], v[48:63]
	v_pk_mul_f32 v[36:37], v[36:37], v[0:1] op_sel_hi:[1,0]
	v_pk_mul_f32 v[38:39], v[38:39], v[0:1] op_sel_hi:[1,0]
	v_pk_mul_f32 v[40:41], v[40:41], v[0:1] op_sel_hi:[1,0]
	v_pk_mul_f32 v[42:43], v[42:43], v[0:1] op_sel_hi:[1,0]
	v_pk_mul_f32 v[44:45], v[44:45], v[0:1] op_sel_hi:[1,0]
	v_pk_mul_f32 v[46:47], v[46:47], v[0:1] op_sel_hi:[1,0]
	v_pk_mul_f32 v[16:17], v[16:17], v[0:1] op_sel_hi:[1,0]
	v_pk_mul_f32 v[18:19], v[18:19], v[0:1] op_sel_hi:[1,0]
	v_mfma_f32_32x32x16_bf16 v[32:47], v[228:231], v[8:11], v[32:47]
	v_pk_mul_f32 v[20:21], v[20:21], v[0:1] op_sel_hi:[1,0]
	v_pk_mul_f32 v[22:23], v[22:23], v[0:1] op_sel_hi:[1,0]
	v_pk_mul_f32 v[24:25], v[24:25], v[0:1] op_sel_hi:[1,0]
	v_pk_mul_f32 v[26:27], v[26:27], v[0:1] op_sel_hi:[1,0]
	v_pk_mul_f32 v[28:29], v[28:29], v[0:1] op_sel_hi:[1,0]
	v_pk_mul_f32 v[30:31], v[30:31], v[0:1] op_sel_hi:[1,0]
	v_mov_b32_e32 v128, v215
	v_mov_b32_e32 v133, v4
	v_mfma_f32_32x32x16_bf16 v[16:31], v[198:201], v[8:11], v[16:31]
	s_waitcnt lgkmcnt(0)
	v_mfma_f32_32x32x16_bf16 v[64:79], v[232:235], v[12:15], v[64:79]
	v_mfma_f32_32x32x16_bf16 v[48:63], v[236:239], v[12:15], v[48:63]
	v_mfma_f32_32x32x16_bf16 v[32:47], v[240:243], v[12:15], v[32:47]
	v_mfma_f32_32x32x16_bf16 v[16:31], v[244:247], v[12:15], v[16:31]
	s_or_b32 s0, s24, s56
	s_and_b32 s0, s0, 0xff
	s_cmp_lg_u32 s0, 0
	s_cbranch_scc1 .LBB0_603

.LBB0_605:
	s_add_i32 s0, s64, 2
	s_cmp_lg_u32 s64, 5
	s_cselect_b32 s0, s0, 1
	s_cmp_lg_u32 s101, 0
	s_cbranch_scc1 .Lna_nobar
	s_waitcnt lgkmcnt(0)
	s_barrier
.Lna_nobar:
	s_mov_b32 s101, 0
	s_cmp_lg_u32 s0, 6
	s_cselect_b32 s64, s0, 0
	s_add_i32 s19, s19, 1
	s_cmp_eq_u32 s21, s19
	v_add_u32_e32 v131, 0x7c, v131
	s_cbranch_scc1 .LBB0_608
	s_mov_b32 s56, s10
	v_mov_b32_e32 v133, v4
	s_branch .LBB0_499

.Lmem_late_bot:
	s_add_i32 s0, s59, 1
	s_cmp_lg_u32 s0, 6
	s_cselect_b32 s59, s0, 0
	s_bitcmp1_b32 s21, 0
	s_branch .Lmem_bot_join
